# plus barrier-complete poll with 16 loads in flight; attention prologue small loads issued with Q loads
# speedup vs baseline: 1.0122x; 1.0003x over previous
.LBB0_214:
	s_or_b64 exec, exec, s[4:5]
	s_cmpk_gt_i32 s38, 0x3ff
	s_mov_b64 s[4:5], -1
	s_cbranch_scc0 .LBB0_232
	s_add_i32 s4, s38, 0xfffffc00
	v_mov_b32_e32 v2, v216
	s_lshr_b32 s4, s4, 6
	s_sub_i32 s7, 15, s4
	v_readfirstlane_b32 s6, v2
	s_ashr_i32 s9, s6, 6
	s_lshl_b32 s4, s38, 9
	s_and_b32 s28, s38, 7
	s_and_b32 s34, s4, 0x7000
	s_lshl_b32 s4, s7, 8
	s_lshl_b32 s5, s9, 5
	v_and_b32_e32 v3, 31, v2
	s_add_i32 s5, s5, s4
	s_lshl_b32 s8, s28, 7
	v_readlane_b32 s4, v255, 4
	v_or_b32_e32 v0, s5, v3
	s_add_u32 s4, s4, s8
	v_readlane_b32 s5, v255, 5
	s_addc_u32 s5, s5, 0
	v_readlane_b32 s12, v255, 6
	s_add_u32 s12, s12, s8
	v_readlane_b32 s13, v255, 7
	v_and_b32_e32 v1, 63, v2
	s_addc_u32 s13, s13, 0
	v_readlane_b32 s14, v255, 8
	s_add_u32 s18, s14, s8
	v_readlane_b32 s8, v255, 9
	v_or_b32_e32 v1, s34, v1
	s_addc_u32 s19, s8, 0
	v_lshlrev_b32_e32 v192, 10, v1
	s_and_b32 s14, s9, 3
	v_bfe_u32 v1, v2, 2, 4
	v_lshl_add_u64 v[6:7], s[12:13], 0, v[192:193]
	s_lshl_b32 s12, s9, 3
	v_lshl_or_b32 v1, s14, 4, v1
	s_ashr_i32 s13, s12, 31
	v_or_b32_e32 v1, s34, v1
	s_ashr_i32 s15, s6, 8
	v_lshl_add_u64 v[162:163], s[12:13], 1, v[6:7]
	v_lshlrev_b32_e32 v192, 10, v1
	s_lshl_b32 s12, s15, 5
	v_lshl_add_u64 v[6:7], s[18:19], 0, v[192:193]
	s_ashr_i32 s13, s12, 31
	v_lshl_add_u64 v[8:9], s[12:13], 1, v[6:7]
	v_lshlrev_b32_e32 v6, 3, v2
	s_lshl_b32 s7, s7, 2
	v_and_b32_e32 v5, 24, v6
	v_sub_u32_e64 v10, s7, 8 clamp
	v_lshlrev_b32_e32 v192, 1, v5
	v_lshl_add_u64 v[166:167], v[8:9], 0, v[192:193]
	v_lshlrev_b32_e32 v192, 16, v10
	s_lshl_b32 s29, s9, 10
	v_lshl_add_u64 v[8:9], v[162:163], 0, v[192:193]
	s_add_i32 s29, s29, 0
	s_mov_b32 s9, m0
	s_mov_b32 m0, s29
	s_nop 0
	global_load_lds_dwordx4 v[8:9], off
	s_mov_b32 m0, s9
	s_lshl_b32 s9, s15, 12
	s_lshl_b32 s12, s14, 10
	s_or_b32 s9, s12, s9
	s_add_i32 s9, s9, 0
	s_max_u32 s8, s7, 8
	v_lshl_add_u64 v[8:9], v[166:167], 0, v[192:193]
	s_add_i32 s36, s9, 0xc000
	s_mov_b32 s12, m0
	s_mov_b32 m0, s36
	s_nop 0
	global_load_lds_dwordx4 v[8:9], off
	s_mov_b32 m0, s12
	s_add_i32 s12, s8, -7
	s_mov_b32 s13, s35
	s_lshl_b64 s[12:13], s[12:13], 16
	v_lshl_add_u64 v[8:9], v[162:163], 0, s[12:13]
	v_ashrrev_i32_e32 v1, 31, v0
	s_add_i32 s14, s29, 0x3000
	s_mov_b32 s15, m0
	s_mov_b32 m0, s14
	s_nop 0
	global_load_lds_dwordx4 v[8:9], off
	s_mov_b32 m0, s15
	v_lshl_add_u64 v[8:9], v[166:167], 0, s[12:13]
	v_lshl_add_u64 v[164:165], v[0:1], 0, s[34:35]
	v_bfe_u32 v4, v2, 5, 1
	s_add_i32 s9, s9, 0xe000
	s_mov_b32 s12, m0
	s_mov_b32 m0, s9
	s_nop 0
	global_load_lds_dwordx4 v[8:9], off
	s_mov_b32 m0, s12
	v_lshlrev_b64 v[8:9], 10, v[164:165]
	v_lshl_add_u64 v[8:9], s[4:5], 0, v[8:9]
	v_lshlrev_b32_e32 v192, 4, v4
	v_lshl_add_u64 v[8:9], v[8:9], 0, v[192:193]
	global_load_dwordx4 v[112:115], v[8:9], off
	global_load_dwordx4 v[116:119], v[8:9], off offset:32
	global_load_dwordx4 v[120:123], v[8:9], off offset:64
	global_load_dwordx4 v[124:127], v[8:9], off offset:96
	s_movk_i32 s4, 0x140
	s_mov_b32 s20, s90
	v_readfirstlane_b32 s34, v10
	v_cmp_gt_i32_e32 vcc, s4, v2
	s_and_b32 s4, s38, 63
	s_lshl_b32 s4, s4, 2
	s_or_b32 s4, s4, 0x27e0
	v_mov_b32_e32 v11, s4
	v_readlane_b32 s12, v253, 26
	v_readlane_b32 s13, v253, 27
	s_nop 4
	global_load_dword v11, v11, s[12:13]
	s_and_saveexec_b64 s[4:5], vcc
	s_cbranch_execz .Lt3_skiprel
	v_or_b32_e32 v6, s28, v6
	v_ashrrev_i32_e32 v7, 31, v6
	v_lshl_add_u64 v[6:7], v[6:7], 2, s[12:13]
	global_load_dword v1, v[6:7], off
.Lt3_skiprel:
	s_or_b64 exec, exec, s[4:5]
	s_waitcnt vmcnt(0)
	s_and_saveexec_b64 s[4:5], vcc
	s_cbranch_execz .LBB0_217
	v_lshl_add_u32 v6, v2, 2, 0
	v_add_u32_e32 v6, 0x14000, v6
	v_mul_f32_e32 v1, 0x3fb8aa3b, v1
	ds_write_b32 v6, v1
.LBB0_217:
	s_or_b64 exec, exec, s[4:5]
	v_mov_b32_e32 v32, 0
	v_mov_b32_e32 v161, 0
	v_lshlrev_b32_e32 v160, 2, v4
	s_sub_i32 s4, s7, s8
	s_add_i32 s4, s4, 12
	s_ashr_i32 s37, s4, 1
	s_cmp_lt_i32 s37, 1
	v_mul_f32_e32 v168, 0x3fb8aa3b, v11
	s_waitcnt vmcnt(0) lgkmcnt(0)
	s_barrier
	s_cbranch_scc1 .LBB0_233
	v_lshlrev_b32_e32 v1, 1, v2
	v_lshrrev_b32_e32 v2, 2, v2
	s_ashr_i32 s39, s6, 7
	v_and_or_b32 v2, v2, 3, v160
	s_add_i32 s39, s39, s7
	v_and_b32_e32 v1, 32, v1
	v_lshlrev_b32_e32 v3, 4, v3
	v_lshlrev_b32_e32 v4, 10, v4
	v_lshl_add_u32 v2, v2, 6, 0
	v_mov_b32_e32 v192, v193
	s_max_i32 s40, s39, 8
	v_add3_u32 v185, 0, v4, v3
	v_add3_u32 v186, v2, v1, v5
	v_sub_u32_e32 v187, v0, v160
	v_mov_b32_e32 v194, v193
	v_mov_b32_e32 v195, v193
	v_mov_b32_e32 v196, v193
	v_mov_b32_e32 v197, v193
	v_mov_b32_e32 v198, v193
	v_mov_b32_e32 v199, v193
	v_mov_b32_e32 v200, v193
	v_mov_b32_e32 v201, v193
	v_mov_b32_e32 v202, v193
	v_mov_b32_e32 v203, v193
	v_mov_b32_e32 v204, v193
	v_mov_b32_e32 v205, v193
	v_mov_b32_e32 v206, v193
	v_mov_b32_e32 v207, v193
	v_mov_b64_e32 v[16:17], v[192:193]
	v_mov_b64_e32 v[0:1], v[192:193]
	s_add_i32 s40, s40, -8
	v_mov_b32_e32 v33, v32
	v_mov_b32_e32 v34, v32
	v_mov_b32_e32 v35, v32
	v_mov_b32_e32 v36, v32
	v_mov_b32_e32 v37, v32
	v_mov_b32_e32 v38, v32
	v_mov_b32_e32 v39, v32
	v_mov_b32_e32 v40, v32
	v_mov_b32_e32 v41, v32
	v_mov_b32_e32 v42, v32
	v_mov_b32_e32 v43, v32
	v_mov_b32_e32 v44, v32
	v_mov_b32_e32 v45, v32
	v_mov_b32_e32 v46, v32
	v_mov_b32_e32 v47, v32
	s_add_i32 s18, s39, -4
	s_mov_b32 s19, 0
	v_mov_b32_e32 v169, v168
	v_mov_b32_e32 v170, v168
	v_mov_b32_e32 v171, v168
	v_mov_b32_e32 v172, v168
	v_mov_b32_e32 v173, v168
	v_mov_b32_e32 v174, v168
	v_mov_b32_e32 v175, v168
	v_mov_b32_e32 v176, v168
	v_mov_b32_e32 v177, v168
	v_mov_b32_e32 v178, v168
	v_mov_b32_e32 v179, v168
	v_mov_b32_e32 v180, v168
	v_mov_b32_e32 v181, v168
	v_mov_b32_e32 v182, v168
	v_mov_b32_e32 v183, v168
	v_mov_b32_e32 v161, 0
	v_mov_b64_e32 v[18:19], v[194:195]
	v_mov_b64_e32 v[20:21], v[196:197]
	v_mov_b64_e32 v[22:23], v[198:199]
	v_mov_b64_e32 v[24:25], v[200:201]
	v_mov_b64_e32 v[26:27], v[202:203]
	v_mov_b64_e32 v[28:29], v[204:205]
	v_mov_b64_e32 v[30:31], v[206:207]
	v_mov_b64_e32 v[2:3], v[194:195]
	v_mov_b64_e32 v[4:5], v[196:197]
	v_mov_b64_e32 v[6:7], v[198:199]
	v_mov_b64_e32 v[8:9], v[200:201]
	v_mov_b64_e32 v[10:11], v[202:203]
	v_mov_b64_e32 v[12:13], v[204:205]
	v_mov_b64_e32 v[14:15], v[206:207]
	s_mov_b32 s90, s20
	s_branch .LBB0_220

.LBB0_241:
	s_ashr_i32 s6, s38, 6
	s_sub_i32 s8, 15, s6
	s_lshl_b32 s6, s8, 8
	s_lshl_b32 s7, s19, 5
	v_and_b32_e32 v8, 31, v3
	s_add_i32 s7, s7, s6
	v_lshrrev_b32_e32 v9, 5, v4
	v_or_b32_e32 v4, s7, v8
	v_readlane_b32 s6, v254, 19
	v_ashrrev_i32_e32 v5, 31, v4
	v_readlane_b32 s7, v254, 20
	s_add_u32 s6, s6, s40
	v_lshl_add_u64 v[132:133], v[4:5], 0, s[34:35]
	s_addc_u32 s7, s7, 0
	v_lshlrev_b64 v[6:7], 10, v[132:133]
	v_lshl_add_u64 v[6:7], s[6:7], 0, v[6:7]
	v_lshlrev_b32_e32 v192, 4, v9
	v_lshl_add_u64 v[6:7], v[6:7], 0, v[192:193]
	global_load_dwordx4 v[80:83], v[6:7], off
	global_load_dwordx4 v[84:87], v[6:7], off offset:32
	global_load_dwordx4 v[88:91], v[6:7], off offset:64
	global_load_dwordx4 v[92:95], v[6:7], off offset:96
	v_lshrrev_b32_e32 v7, 2, v3
	v_lshl_add_u64 v[134:135], v[0:1], 2, s[4:5]
	v_lshl_add_u64 v[0:1], v[4:5], 2, s[4:5]
	global_load_dword v32, v[0:1], off
	v_lshlrev_b32_e32 v160, 2, v9
	v_readlane_b32 s4, v253, 20
	v_lshlrev_b32_e32 v3, 1, v3
	v_and_or_b32 v5, v7, 3, v160
	v_add_u32_e32 v141, s4, v192
	s_lshl_b32 s4, s8, 2
	s_ashr_i32 s18, s18, 7
	v_and_b32_e32 v3, 32, v3
	s_add_i32 s18, s18, s4
	v_mov_b32_e32 v6, v193
	s_add_i32 s4, s4, 4
	v_mov_b32_e32 v192, v193
	v_mov_b32_e32 v194, v193
	v_mov_b32_e32 v195, v193
	v_mov_b32_e32 v196, v193
	v_mov_b32_e32 v197, v193
	v_mov_b32_e32 v198, v193
	v_mov_b32_e32 v199, v193
	v_mov_b32_e32 v200, v193
	v_mov_b32_e32 v201, v193
	v_mov_b32_e32 v202, v193
	v_mov_b32_e32 v203, v193
	v_mov_b32_e32 v204, v193
	v_mov_b32_e32 v205, v193
	v_mov_b32_e32 v206, v193
	v_mov_b32_e32 v207, v193
	s_lshr_b32 s19, s4, 1
	s_mov_b32 s37, 0
	v_mov_b32_e32 v143, 0
	s_waitcnt vmcnt(3)
	s_waitcnt vmcnt(2)
	s_waitcnt vmcnt(1)
	s_waitcnt vmcnt(0)
	v_lshlrev_b32_e32 v0, 10, v9
	v_lshlrev_b32_e32 v1, 4, v8
	v_add3_u32 v140, 0, v0, v1
	v_lshl_add_u32 v0, v5, 6, 0
	v_add3_u32 v142, v0, v3, v2
	v_lshl_or_b32 v0, s18, 6, v160
	v_cmp_gt_i32_e64 s[42:43], v0, v4
	v_cmp_lt_i32_e64 s[44:45], v0, v4
	v_or_b32_e32 v1, 3, v0
	v_or_b32_e32 v2, 2, v0
	v_or_b32_e32 v3, 9, v0
	v_or_b32_e32 v5, 8, v0
	v_or_b32_e32 v7, 11, v0
	v_or_b32_e32 v8, 10, v0
	v_or_b32_e32 v9, 17, v0
	v_or_b32_e32 v10, 16, v0
	v_or_b32_e32 v11, 19, v0
	v_or_b32_e32 v12, 18, v0
	v_or_b32_e32 v13, 25, v0
	v_or_b32_e32 v14, 24, v0
	v_or_b32_e32 v15, 27, v0
	v_or_b32_e32 v16, 26, v0
	v_or_b32_e32 v17, 32, v0
	v_or_b32_e32 v18, 33, v0
	v_or_b32_e32 v19, 34, v0
	v_or_b32_e32 v20, 35, v0
	v_or_b32_e32 v21, 40, v0
	v_or_b32_e32 v22, 41, v0
	v_or_b32_e32 v23, 42, v0
	v_or_b32_e32 v24, 43, v0
	v_or_b32_e32 v25, 48, v0
	v_or_b32_e32 v26, 49, v0
	v_or_b32_e32 v27, 50, v0
	v_or_b32_e32 v28, 51, v0
	v_or_b32_e32 v29, 56, v0
	v_or_b32_e32 v30, 57, v0
	v_or_b32_e32 v31, 58, v0
	v_or_b32_e32 v0, 59, v0
	s_waitcnt vmcnt(0)
	s_waitcnt vmcnt(0) lgkmcnt(0)
	s_barrier
	v_cmp_gt_i32_e64 s[46:47], v1, v4
	v_cmp_gt_i32_e64 s[48:49], v2, v4
	v_cmp_gt_i32_e64 s[50:51], v3, v4
	v_cmp_gt_i32_e64 s[52:53], v5, v4
	v_cmp_gt_i32_e64 s[54:55], v7, v4
	v_cmp_gt_i32_e64 s[56:57], v8, v4
	v_cmp_gt_i32_e64 s[58:59], v9, v4
	v_cmp_gt_i32_e64 s[60:61], v10, v4
	v_cmp_gt_i32_e64 s[62:63], v11, v4
	v_cmp_gt_i32_e64 s[64:65], v12, v4
	v_cmp_gt_i32_e64 s[66:67], v13, v4
	v_cmp_gt_i32_e64 s[68:69], v14, v4
	v_cmp_gt_i32_e64 s[70:71], v15, v4
	v_cmp_gt_i32_e64 s[72:73], v16, v4
	v_cmp_gt_i32_e64 s[74:75], v0, v4
	v_cmp_gt_i32_e64 s[76:77], v31, v4
	v_cmp_gt_i32_e64 s[78:79], v30, v4
	v_cmp_gt_i32_e64 s[80:81], v29, v4
	v_cmp_gt_i32_e64 s[82:83], v28, v4
	v_cmp_gt_i32_e64 s[84:85], v27, v4
	v_cmp_gt_i32_e64 s[86:87], v26, v4
	v_cmp_gt_i32_e64 s[88:89], v25, v4
	v_cmp_gt_i32_e64 s[90:91], v24, v4
	v_cmp_gt_i32_e64 s[92:93], v23, v4
	v_cmp_gt_i32_e64 s[94:95], v22, v4
	v_cmp_gt_i32_e64 s[96:97], v21, v4
	v_cmp_gt_i32_e64 s[98:99], v20, v4
	v_cmp_gt_i32_e64 s[38:39], v19, v4
	v_cmp_gt_i32_e64 s[4:5], v18, v4
	v_cmp_gt_i32_e64 s[6:7], v17, v4
	v_mov_b64_e32 v[16:17], v[192:193]
	v_mov_b64_e32 v[0:1], v[192:193]
	v_mov_b32_e32 v33, v32
	v_mov_b32_e32 v34, v32
	v_mov_b32_e32 v35, v32
	v_mov_b32_e32 v36, v32
	v_mov_b32_e32 v37, v32
	v_mov_b32_e32 v38, v32
	v_mov_b32_e32 v39, v32
	v_mov_b32_e32 v40, v32
	v_mov_b32_e32 v41, v32
	v_mov_b32_e32 v42, v32
	v_mov_b32_e32 v43, v32
	v_mov_b32_e32 v44, v32
	v_mov_b32_e32 v45, v32
	v_mov_b32_e32 v46, v32
	v_mov_b32_e32 v47, v32
	v_mov_b64_e32 v[18:19], v[194:195]
	v_mov_b64_e32 v[20:21], v[196:197]
	v_mov_b64_e32 v[22:23], v[198:199]
	v_mov_b64_e32 v[24:25], v[200:201]
	v_mov_b64_e32 v[26:27], v[202:203]
	v_mov_b64_e32 v[28:29], v[204:205]
	v_mov_b64_e32 v[30:31], v[206:207]
	v_mov_b64_e32 v[2:3], v[194:195]
	v_mov_b64_e32 v[4:5], v[196:197]
	v_mov_b64_e32 v[6:7], v[198:199]
	v_mov_b64_e32 v[8:9], v[200:201]
	v_mov_b64_e32 v[10:11], v[202:203]
	v_mov_b64_e32 v[12:13], v[204:205]
	v_mov_b64_e32 v[14:15], v[206:207]
	s_branch .LBB0_243

.LBB0_492:
	global_load_dword v2, v193, s[14:15] sc1
	s_waitcnt lgkmcnt(0)
	global_load_dword v0, v193, s[14:15] offset:256 sc1
	global_load_dword v1, v193, s[14:15] offset:512 sc1
	global_load_dword v3, v193, s[14:15] offset:768 sc1
	global_load_dword v4, v193, s[14:15] offset:1024 sc1
	global_load_dword v5, v193, s[14:15] offset:1280 sc1
	global_load_dword v6, v193, s[14:15] offset:1536 sc1
	global_load_dword v7, v193, s[14:15] offset:1792 sc1
	global_load_dword v8, v193, s[14:15] offset:2048 sc1
	global_load_dword v9, v193, s[14:15] offset:2304 sc1
	global_load_dword v10, v193, s[14:15] offset:2560 sc1
	global_load_dword v11, v193, s[14:15] offset:2816 sc1
	global_load_dword v12, v193, s[14:15] offset:3072 sc1
	global_load_dword v13, v193, s[14:15] offset:3328 sc1
	global_load_dword v14, v193, s[14:15] offset:3584 sc1
	global_load_dword v15, v193, s[14:15] offset:3840 sc1
	v_readlane_b32 s8, v253, 14
	s_waitcnt vmcnt(0)
	v_add_u32_e32 v16, v0, v2
	v_add_u32_e32 v16, v16, v1
	v_add_u32_e32 v16, v16, v3
	v_add_u32_e32 v16, v16, v4
	v_add_u32_e32 v16, v16, v5
	v_add_u32_e32 v16, v16, v6
	v_add_u32_e32 v16, v16, v7
	v_add_u32_e32 v16, v16, v8
	v_add_u32_e32 v16, v16, v9
	v_add_u32_e32 v16, v16, v10
	v_add_u32_e32 v16, v16, v11
	v_add_u32_e32 v16, v16, v12
	v_add_u32_e32 v16, v16, v13
	v_add_u32_e32 v16, v16, v14
	v_add_u32_e32 v16, v16, v15
	s_mov_b64 s[6:7], -1
	v_cmp_eq_u32_e32 vcc, s8, v16
	s_mov_b64 s[8:9], -1
	s_cbranch_vccnz .LBB0_491
	s_and_b32 s6, s10, 0xff
	s_cmp_eq_u32 s6, 0
	s_mov_b64 s[6:7], -1
	s_mov_b64 s[28:29], -1
	s_sleep 1
	s_cbranch_scc1 .LBB0_496
	s_and_b64 vcc, exec, s[28:29]
	s_cbranch_vccz .LBB0_491
